# v15 + residual (kind 1) epilogue also drains right after each row group's f32 stores
# speedup vs baseline: 1.0017x; 1.0017x over previous
;     static __device__ __forceinline__ void run(const f32x4 (&acc)[2][2][4][2], const Unit& u, int wr, int wc, int fr, int fq, const float* xin, float* xout, const float* gate, float gs, const float* lazy_ssq, const float* lazy_g, ...
;     ...
;                 gv[n] = *(const f32x4*)(gate + (b * 9216u + col + 4 * n)) * gs;
;                 lg[n] = (f32x4){1.f, 1.f, 1.f, 1.f}; if (LAZY) lg[n] = *(const f32x4*)(lazy_g + col + 4 * n);
;                 wv[n] = (f32x4){0.f, 0.f, 0.f, 0.f}; w2[n] = (f32x4){1.f, 1.f, 1.f, 1.f};
;                 if (aout) { wv[n] = *(const f32x4*)(wg + col + 4 * n) * (*(const f32x4*)(wsc + (b * 9216u + col + 4 * n)) + 1.0f); if (WG2) { w2[n] = *(const f32x4*)(wg2 + col + 4 * n); wv[n] = wv[n] * w2[n]; } }
;             }
;             f32x4 xq[2][2][2];
;     ...
;             constexpr bool DEEP = !LAZY && !WG2;
;             if (DEEP) RES_LD(0, 0);
; #pragma unroll
;             for (int pp = 0; pp < 4; ++pp) {
;                 if (DEEP) { if (pp < 3) RES_LD((pp + 1) & 1, pp + 1); } else RES_LD(pp & 1, pp);
; #pragma unroll
;                 for (int j = 0; j < 2; ++j) { const int i_ = 2 * pp + j, ai = i_ >> 2, m = i_ & 3; const unsigned off = (row0 + ai * HALF + m * 16) * 1024u + col;
;                     const f32x4 xi0 = xq[pp & 1][j][0], xi1 = xq[pp & 1][j][1];
;                     f32x4 xo0 = gv[0] * acc[ai][bj][m][0], xo1 = gv[1] * acc[ai][bj][m][1];
;                     if (LAZY) { xo0 = xo0 + xi0 * lg[0] * rl[ai][m]; xo1 = xo1 + xi1 * lg[1] * rl[ai][m]; } else { xo0 = xo0 + xi0; xo1 = xo1 + xi1; }
;                     *(f32x4*)(xout + off) = xo0; *(f32x4*)(xout + off + 4) = xo1;
;                     if (aout) { const f32x4 a0 = xo0 * wv[0], a1 = xo1 * wv[1]; u32x4 w; w.x = cvt_pk_bf16(a0[0], a0[1]); w.y = cvt_pk_bf16(a0[2], a0[3]); w.z = cvt_pk_bf16(a1[0], a1[1]); w.w = cvt_pk_bf16(a1[2], a1[3]);
;                         *(u32x4*)(aout + off) = w;
;                         sq[ai][m] += ((xo0[0] * xo0[0] + xo0[1] * xo0[1]) + (xo0[2] * xo0[2] + xo0[3] * xo0[3])) + ((xo1[0] * xo1[0] + xo1[1] * xo1[1]) + (xo1[2] * xo1[2] + xo1[3] * xo1[3]));
;                         if (WG2) { const f32x4 b0 = xo0 * w2[0], b1 = xo1 * w2[1]; sqb[ai][m] += ((b0[0] * b0[0] + b0[1] * b0[1]) + (b0[2] * b0[2] + b0[3] * b0[3])) + ((b1[0] * b1[0] + b1[1] * b1[1]) + (b1[2] * b1[2] + b1[3] * b1[3])); } } }
.LBB0_487:
	s_lshl_b32 s42, s63, 8
	s_lshl_b32 s43, s65, 6
	s_add_i32 s43, s43, s42
	v_or_b32_e32 v172, s43, v230
	v_lshlrev_b32_e32 v207, 10, v172
	v_add_u32_e32 v176, v180, v207
	v_lshlrev_b64 v[204:205], 2, v[176:177]
	s_waitcnt vmcnt(0)
	v_pk_mul_f32 v[196:197], s[36:37], v[128:129] op_sel_hi:[0,1]
	v_lshl_add_u64 v[128:129], s[34:35], 0, v[204:205]
	v_add_u32_e32 v202, 0x4000, v176
	v_mov_b32_e32 v203, v177
	global_load_dwordx4 v[152:155], v[128:129], off offset:16
	global_load_dwordx4 v[156:159], v[128:129], off
	v_lshl_add_u64 v[128:129], v[202:203], 2, s[34:35]
	v_add_u32_e32 v200, 0x8000, v176
	v_mov_b32_e32 v201, v177
	v_add_u32_e32 v198, 0xc000, v176
	v_mov_b32_e32 v199, v177
	v_pk_mul_f32 v[190:191], s[36:37], v[132:133] op_sel_hi:[0,1]
	global_load_dwordx4 v[136:139], v[128:129], off offset:16
	global_load_dwordx4 v[144:147], v[128:129], off
	v_lshl_add_u64 v[128:129], v[200:201], 2, s[34:35]
	v_lshl_add_u64 v[132:133], v[198:199], 2, s[34:35]
	v_pk_mul_f32 v[192:193], s[36:37], v[134:135] op_sel_hi:[0,1]
	v_pk_mul_f32 v[194:195], s[36:37], v[130:131] op_sel_hi:[0,1]
	global_load_dwordx4 v[140:143], v[128:129], off offset:16
	global_load_dwordx4 v[148:151], v[128:129], off
	s_nop 0
	global_load_dwordx4 v[128:131], v[132:133], off offset:16
	s_nop 0
	global_load_dwordx4 v[132:135], v[132:133], off
	v_lshl_add_u64 v[204:205], s[28:29], 0, v[204:205]
	s_and_b64 vcc, exec, s[8:9]
	v_mov_b32_e32 v173, 0
	s_waitcnt vmcnt(0)
	v_pk_fma_f32 v[154:155], v[122:123], v[192:193], v[154:155]
	s_waitcnt vmcnt(0)
	v_pk_fma_f32 v[158:159], v[126:127], v[194:195], v[158:159]
	v_pk_fma_f32 v[156:157], v[124:125], v[196:197], v[156:157]
	v_pk_fma_f32 v[152:153], v[120:121], v[190:191], v[152:153]
	global_store_dwordx4 v[204:205], v[156:159], off
	global_store_dwordx4 v[204:205], v[152:155], off offset:16
	s_waitcnt vmcnt(0)
	v_mov_b32_e32 v204, 0
	s_cbranch_vccnz .LBB0_489
	v_pk_mul_f32 v[210:211], v[184:185], v[158:159]
	v_pk_mul_f32 v[208:209], v[182:183], v[156:157]
	v_pk_mul_f32 v[212:213], v[188:189], v[154:155]
	v_pk_mul_f32 v[214:215], v[186:187], v[152:153]
	v_cvt_pk_bf16_f32 v208, v208, v209
	v_cvt_pk_bf16_f32 v209, v210, v211
	s_nop 0
	v_cvt_pk_bf16_f32 v210, v214, v215
	v_cvt_pk_bf16_f32 v211, v212, v213
	v_lshl_add_u64 v[212:213], v[176:177], 1, s[26:27]
	global_store_dwordx4 v[212:213], v[208:211], off
	s_nop 1
	v_mov_b32_e32 v209, v152
	v_mov_b32_e32 v152, v157
	v_mov_b32_e32 v157, v154
	v_mov_b32_e32 v154, v159
	v_mov_b32_e32 v208, v156
	v_pk_mul_f32 v[152:153], v[152:153], v[152:153]
	v_mov_b32_e32 v156, v158
	v_pk_mul_f32 v[154:155], v[154:155], v[154:155]
	v_pk_fma_f32 v[152:153], v[208:209], v[208:209], v[152:153]
	v_pk_fma_f32 v[154:155], v[156:157], v[156:157], v[154:155]
	s_nop 0
	v_pk_add_f32 v[152:153], v[152:153], v[154:155]
	s_nop 0
	v_add_f32_e32 v173, v152, v153
.LBB0_489:
	s_waitcnt vmcnt(0)
	v_pk_fma_f32 v[146:147], v[110:111], v[194:195], v[146:147]
	v_pk_fma_f32 v[144:145], v[108:109], v[196:197], v[144:145]
	v_pk_fma_f32 v[138:139], v[106:107], v[192:193], v[138:139]
	v_pk_fma_f32 v[136:137], v[104:105], v[190:191], v[136:137]
	v_lshl_add_u64 v[152:153], v[202:203], 2, s[28:29]
	s_and_b64 vcc, exec, s[8:9]
	global_store_dwordx4 v[152:153], v[144:147], off
	global_store_dwordx4 v[152:153], v[136:139], off offset:16
	s_waitcnt vmcnt(0)
	s_cbranch_vccnz .LBB0_491
	v_pk_mul_f32 v[154:155], v[184:185], v[146:147]
	v_pk_mul_f32 v[152:153], v[182:183], v[144:145]
	v_pk_mul_f32 v[156:157], v[188:189], v[138:139]
	v_pk_mul_f32 v[158:159], v[186:187], v[136:137]
	v_cvt_pk_bf16_f32 v152, v152, v153
	v_cvt_pk_bf16_f32 v153, v154, v155
	s_nop 0
	v_cvt_pk_bf16_f32 v154, v158, v159
	v_cvt_pk_bf16_f32 v155, v156, v157
	v_lshl_add_u64 v[156:157], v[202:203], 1, s[26:27]
	global_store_dwordx4 v[156:157], v[152:155], off
	s_nop 1
	v_mov_b32_e32 v153, v136
	v_mov_b32_e32 v136, v145
	v_mov_b32_e32 v145, v138
	v_mov_b32_e32 v138, v147
	v_mov_b32_e32 v152, v144
	v_pk_mul_f32 v[136:137], v[136:137], v[136:137]
	v_mov_b32_e32 v144, v146
	v_pk_mul_f32 v[138:139], v[138:139], v[138:139]
	v_pk_fma_f32 v[136:137], v[152:153], v[152:153], v[136:137]
	v_pk_fma_f32 v[138:139], v[144:145], v[144:145], v[138:139]
	s_nop 0
	v_pk_add_f32 v[136:137], v[136:137], v[138:139]
	s_nop 0
	v_add_f32_e32 v204, v136, v137
.LBB0_491:
	v_add_u32_e32 v208, 0x20000, v207
	v_add_u32_e32 v202, v208, v180
	v_mov_b32_e32 v203, v177
	v_lshl_add_u64 v[136:137], v[202:203], 2, s[34:35]
	global_load_dwordx4 v[152:155], v[136:137], off offset:16
	global_load_dwordx4 v[156:159], v[136:137], off
	v_add_u32_e32 v136, 0x4000, v202
	v_mov_b32_e32 v137, v177
	v_lshl_add_u64 v[144:145], v[136:137], 2, s[34:35]
	global_load_dwordx4 v[136:139], v[144:145], off offset:16
	s_nop 0
	global_load_dwordx4 v[144:147], v[144:145], off
	s_waitcnt vmcnt(0)
	v_pk_fma_f32 v[150:151], v[94:95], v[194:195], v[150:151]
	v_pk_fma_f32 v[148:149], v[92:93], v[196:197], v[148:149]
	v_pk_fma_f32 v[142:143], v[90:91], v[192:193], v[142:143]
	v_pk_fma_f32 v[140:141], v[88:89], v[190:191], v[140:141]
	v_lshl_add_u64 v[210:211], v[200:201], 2, s[28:29]
	v_mov_b32_e32 v203, 0
	s_and_b64 vcc, exec, s[8:9]
	v_mov_b32_e32 v205, 0
	global_store_dwordx4 v[210:211], v[148:151], off
	global_store_dwordx4 v[210:211], v[140:143], off offset:16
	s_waitcnt vmcnt(0)
	s_cbranch_vccnz .LBB0_493
	v_pk_mul_f32 v[212:213], v[184:185], v[150:151]
	v_pk_mul_f32 v[210:211], v[182:183], v[148:149]
	v_lshl_add_u64 v[200:201], v[200:201], 1, s[26:27]
	v_pk_mul_f32 v[214:215], v[188:189], v[142:143]
	v_pk_mul_f32 v[232:233], v[186:187], v[140:141]
	v_cvt_pk_bf16_f32 v210, v210, v211
	v_cvt_pk_bf16_f32 v211, v212, v213
	s_nop 0
	v_cvt_pk_bf16_f32 v212, v232, v233
	v_cvt_pk_bf16_f32 v213, v214, v215
	global_store_dwordx4 v[200:201], v[210:213], off
	v_mov_b32_e32 v201, v140
	v_mov_b32_e32 v140, v149
	v_mov_b32_e32 v149, v142
	v_mov_b32_e32 v142, v151
	v_mov_b32_e32 v200, v148
	v_pk_mul_f32 v[140:141], v[140:141], v[140:141]
	v_mov_b32_e32 v148, v150
	v_pk_mul_f32 v[142:143], v[142:143], v[142:143]
	v_pk_fma_f32 v[140:141], v[200:201], v[200:201], v[140:141]
	v_pk_fma_f32 v[142:143], v[148:149], v[148:149], v[142:143]
	s_nop 0
	v_pk_add_f32 v[140:141], v[140:141], v[142:143]
	s_nop 0
	v_add_f32_e32 v205, v140, v141
; __device__ __forceinline__ unsigned cvt_pk_bf16(float lo, float hi) { unsigned r; asm volatile("v_cvt_pk_bf16_f32 %0, %1, %2" : "=v"(r) : "v"(lo), "v"(hi)); return r; }
; #define RES_LD(buf, pp) do { _Pragma("unroll") for (int j = 0; j < 2; ++j) { const int i_ = 2 * (pp) + j; const unsigned off_ = (row0 + (i_ >> 2) * HALF + (i_ & 3) * 16) * 1024u + col; \
;                 xq[buf][j][0] = *(const f32x4*)(xin + off_); xq[buf][j][1] = *(const f32x4*)(xin + off_ + 4); } } while (0)
;     static __device__ __forceinline__ void run(const f32x4 (&acc)[2][2][4][2], const Unit& u, int wr, int wc, int fr, int fq, const float* xin, float* xout, const float* gate, float gs, const float* lazy_ssq, const float* lazy_g, ...
;     ...
;             constexpr bool DEEP = !LAZY && !WG2;
;             if (DEEP) RES_LD(0, 0);
; #pragma unroll
;             for (int pp = 0; pp < 4; ++pp) {
;                 if (DEEP) { if (pp < 3) RES_LD((pp + 1) & 1, pp + 1); } else RES_LD(pp & 1, pp);
; #pragma unroll
;                 for (int j = 0; j < 2; ++j) { const int i_ = 2 * pp + j, ai = i_ >> 2, m = i_ & 3; const unsigned off = (row0 + ai * HALF + m * 16) * 1024u + col;
;                     const f32x4 xi0 = xq[pp & 1][j][0], xi1 = xq[pp & 1][j][1];
;                     f32x4 xo0 = gv[0] * acc[ai][bj][m][0], xo1 = gv[1] * acc[ai][bj][m][1];
;                     if (LAZY) { xo0 = xo0 + xi0 * lg[0] * rl[ai][m]; xo1 = xo1 + xi1 * lg[1] * rl[ai][m]; } else { xo0 = xo0 + xi0; xo1 = xo1 + xi1; }
;                     *(f32x4*)(xout + off) = xo0; *(f32x4*)(xout + off + 4) = xo1;
;                     if (aout) { const f32x4 a0 = xo0 * wv[0], a1 = xo1 * wv[1]; u32x4 w; w.x = cvt_pk_bf16(a0[0], a0[1]); w.y = cvt_pk_bf16(a0[2], a0[3]); w.z = cvt_pk_bf16(a1[0], a1[1]); w.w = cvt_pk_bf16(a1[2], a1[3]);
;                         *(u32x4*)(aout + off) = w;
;                         sq[ai][m] += ((xo0[0] * xo0[0] + xo0[1] * xo0[1]) + (xo0[2] * xo0[2] + xo0[3] * xo0[3])) + ((xo1[0] * xo1[0] + xo1[1] * xo1[1]) + (xo1[2] * xo1[2] + xo1[3] * xo1[3]));
;                         if (WG2) { const f32x4 b0 = xo0 * w2[0], b1 = xo1 * w2[1]; sqb[ai][m] += ((b0[0] * b0[0] + b0[1] * b0[1]) + (b0[2] * b0[2] + b0[3] * b0[3])) + ((b1[0] * b1[0] + b1[1] * b1[1]) + (b1[2] * b1[2] + b1[3] * b1[3])); } } }
.LBB0_493:
	s_waitcnt vmcnt(0)
	v_pk_fma_f32 v[134:135], v[78:79], v[194:195], v[134:135]
	v_pk_fma_f32 v[132:133], v[76:77], v[196:197], v[132:133]
	v_pk_fma_f32 v[130:131], v[74:75], v[192:193], v[130:131]
	v_pk_fma_f32 v[128:129], v[72:73], v[190:191], v[128:129]
	v_lshl_add_u64 v[140:141], v[198:199], 2, s[28:29]
	s_and_b64 vcc, exec, s[8:9]
	global_store_dwordx4 v[140:141], v[132:135], off
	global_store_dwordx4 v[140:141], v[128:131], off offset:16
	s_waitcnt vmcnt(0)
	s_cbranch_vccnz .LBB0_495
	v_pk_mul_f32 v[142:143], v[184:185], v[134:135]
	v_pk_mul_f32 v[140:141], v[182:183], v[132:133]
	v_pk_mul_f32 v[148:149], v[188:189], v[130:131]
	v_pk_mul_f32 v[150:151], v[186:187], v[128:129]
	v_cvt_pk_bf16_f32 v140, v140, v141
	v_cvt_pk_bf16_f32 v141, v142, v143
	s_nop 0
	v_cvt_pk_bf16_f32 v142, v150, v151
	v_cvt_pk_bf16_f32 v143, v148, v149
	v_lshl_add_u64 v[148:149], v[198:199], 1, s[26:27]
	global_store_dwordx4 v[148:149], v[140:143], off
	s_nop 1
	v_mov_b32_e32 v141, v128
	v_mov_b32_e32 v128, v133
	v_mov_b32_e32 v133, v130
	v_mov_b32_e32 v130, v135
	v_mov_b32_e32 v140, v132
	v_pk_mul_f32 v[128:129], v[128:129], v[128:129]
	v_mov_b32_e32 v132, v134
	v_pk_mul_f32 v[130:131], v[130:131], v[130:131]
	v_pk_fma_f32 v[128:129], v[140:141], v[140:141], v[128:129]
	v_pk_fma_f32 v[130:131], v[132:133], v[132:133], v[130:131]
	s_nop 0
	v_pk_add_f32 v[128:129], v[128:129], v[130:131]
	s_nop 0
	v_add_f32_e32 v203, v128, v129
.LBB0_495:
	s_nop 0
	v_add_u32_e32 v128, 0x8000, v202
	v_mov_b32_e32 v129, v177
	v_lshl_add_u64 v[128:129], v[128:129], 2, s[34:35]
	global_load_dwordx4 v[140:143], v[128:129], off offset:16
	global_load_dwordx4 v[148:151], v[128:129], off
	v_add_u32_e32 v128, 0xc000, v202
	v_mov_b32_e32 v129, v177
	v_lshl_add_u64 v[132:133], v[128:129], 2, s[34:35]
	global_load_dwordx4 v[128:131], v[132:133], off offset:16
	s_nop 0
	global_load_dwordx4 v[132:135], v[132:133], off
	v_add_u32_e32 v198, 0x20000, v176
	v_mov_b32_e32 v199, v177
	s_waitcnt vmcnt(0)
	v_pk_fma_f32 v[158:159], v[62:63], v[194:195], v[158:159]
	v_pk_fma_f32 v[156:157], v[60:61], v[196:197], v[156:157]
	v_lshl_add_u64 v[200:201], v[198:199], 2, s[28:29]
	v_pk_fma_f32 v[154:155], v[58:59], v[192:193], v[154:155]
	v_pk_fma_f32 v[152:153], v[56:57], v[190:191], v[152:153]
	global_store_dwordx4 v[200:201], v[156:159], off
	global_store_dwordx4 v[200:201], v[152:155], off offset:16
	s_waitcnt vmcnt(0)
	v_mov_b32_e32 v200, 0
	s_and_b64 vcc, exec, s[8:9]
	v_mov_b32_e32 v201, 0
	s_cbranch_vccnz .LBB0_497
	v_pk_mul_f32 v[212:213], v[184:185], v[158:159]
	v_pk_mul_f32 v[210:211], v[182:183], v[156:157]
	v_lshl_add_u64 v[198:199], v[198:199], 1, s[26:27]
	v_pk_mul_f32 v[214:215], v[188:189], v[154:155]
	v_pk_mul_f32 v[232:233], v[186:187], v[152:153]
	v_cvt_pk_bf16_f32 v210, v210, v211
	v_cvt_pk_bf16_f32 v211, v212, v213
	s_nop 0
	v_cvt_pk_bf16_f32 v212, v232, v233
	v_cvt_pk_bf16_f32 v213, v214, v215
	global_store_dwordx4 v[198:199], v[210:213], off
	v_mov_b32_e32 v199, v152
	v_mov_b32_e32 v152, v157
	v_mov_b32_e32 v157, v154
	v_mov_b32_e32 v154, v159
	v_mov_b32_e32 v198, v156
	v_pk_mul_f32 v[152:153], v[152:153], v[152:153]
	v_mov_b32_e32 v156, v158
	v_pk_mul_f32 v[154:155], v[154:155], v[154:155]
	v_pk_fma_f32 v[152:153], v[198:199], v[198:199], v[152:153]
	v_pk_fma_f32 v[154:155], v[156:157], v[156:157], v[154:155]
	s_nop 0
	v_pk_add_f32 v[152:153], v[152:153], v[154:155]
	s_nop 0
	v_add_f32_e32 v201, v152, v153
; __device__ __forceinline__ unsigned cvt_pk_bf16(float lo, float hi) { unsigned r; asm volatile("v_cvt_pk_bf16_f32 %0, %1, %2" : "=v"(r) : "v"(lo), "v"(hi)); return r; }
;     static __device__ __forceinline__ void run(const f32x4 (&acc)[2][2][4][2], const Unit& u, int wr, int wc, int fr, int fq, const float* xin, float* xout, const float* gate, float gs, const float* lazy_ssq, const float* lazy_g, ...
;     ...
;                 for (int j = 0; j < 2; ++j) { const int i_ = 2 * pp + j, ai = i_ >> 2, m = i_ & 3; const unsigned off = (row0 + ai * HALF + m * 16) * 1024u + col;
;                     const f32x4 xi0 = xq[pp & 1][j][0], xi1 = xq[pp & 1][j][1];
;                     f32x4 xo0 = gv[0] * acc[ai][bj][m][0], xo1 = gv[1] * acc[ai][bj][m][1];
;                     if (LAZY) { xo0 = xo0 + xi0 * lg[0] * rl[ai][m]; xo1 = xo1 + xi1 * lg[1] * rl[ai][m]; } else { xo0 = xo0 + xi0; xo1 = xo1 + xi1; }
;                     *(f32x4*)(xout + off) = xo0; *(f32x4*)(xout + off + 4) = xo1;
;                     if (aout) { const f32x4 a0 = xo0 * wv[0], a1 = xo1 * wv[1]; u32x4 w; w.x = cvt_pk_bf16(a0[0], a0[1]); w.y = cvt_pk_bf16(a0[2], a0[3]); w.z = cvt_pk_bf16(a1[0], a1[1]); w.w = cvt_pk_bf16(a1[2], a1[3]);
;                         *(u32x4*)(aout + off) = w;
;                         sq[ai][m] += ((xo0[0] * xo0[0] + xo0[1] * xo0[1]) + (xo0[2] * xo0[2] + xo0[3] * xo0[3])) + ((xo1[0] * xo1[0] + xo1[1] * xo1[1]) + (xo1[2] * xo1[2] + xo1[3] * xo1[3]));
;                         if (WG2) { const f32x4 b0 = xo0 * w2[0], b1 = xo1 * w2[1]; sqb[ai][m] += ((b0[0] * b0[0] + b0[1] * b0[1]) + (b0[2] * b0[2] + b0[3] * b0[3])) + ((b1[0] * b1[0] + b1[1] * b1[1]) + (b1[2] * b1[2] + b1[3] * b1[3])); } } }
.LBB0_497:
	v_add_u32_e32 v152, 0x24000, v176
	v_mov_b32_e32 v153, v177
	s_waitcnt vmcnt(0)
	v_pk_fma_f32 v[146:147], v[46:47], v[194:195], v[146:147]
	v_pk_fma_f32 v[144:145], v[44:45], v[196:197], v[144:145]
	v_pk_fma_f32 v[138:139], v[42:43], v[192:193], v[138:139]
	v_pk_fma_f32 v[136:137], v[40:41], v[190:191], v[136:137]
	v_lshl_add_u64 v[154:155], v[152:153], 2, s[28:29]
	s_and_b64 vcc, exec, s[8:9]
	global_store_dwordx4 v[154:155], v[144:147], off
	global_store_dwordx4 v[154:155], v[136:139], off offset:16
	s_waitcnt vmcnt(0)
	s_cbranch_vccnz .LBB0_499
	v_pk_mul_f32 v[156:157], v[184:185], v[146:147]
	v_pk_mul_f32 v[154:155], v[182:183], v[144:145]
	v_lshl_add_u64 v[152:153], v[152:153], 1, s[26:27]
	v_pk_mul_f32 v[158:159], v[188:189], v[138:139]
	v_pk_mul_f32 v[198:199], v[186:187], v[136:137]
	v_cvt_pk_bf16_f32 v154, v154, v155
	v_cvt_pk_bf16_f32 v155, v156, v157
	s_nop 0
	v_cvt_pk_bf16_f32 v156, v198, v199
	v_cvt_pk_bf16_f32 v157, v158, v159
	global_store_dwordx4 v[152:153], v[154:157], off
	v_mov_b32_e32 v153, v136
	v_mov_b32_e32 v136, v145
	v_mov_b32_e32 v145, v138
	v_mov_b32_e32 v138, v147
	v_mov_b32_e32 v152, v144
	v_pk_mul_f32 v[136:137], v[136:137], v[136:137]
	v_mov_b32_e32 v144, v146
	v_pk_mul_f32 v[138:139], v[138:139], v[138:139]
	v_pk_fma_f32 v[136:137], v[152:153], v[152:153], v[136:137]
	v_pk_fma_f32 v[138:139], v[144:145], v[144:145], v[138:139]
	s_nop 0
	v_pk_add_f32 v[136:137], v[136:137], v[138:139]
	s_nop 0
	v_add_f32_e32 v200, v136, v137
.LBB0_499:
	v_add_u32_e32 v144, 0x28000, v176
	v_mov_b32_e32 v145, v177
	s_waitcnt vmcnt(0)
	v_pk_fma_f32 v[138:139], v[30:31], v[194:195], v[150:151]
	v_pk_fma_f32 v[136:137], v[28:29], v[196:197], v[148:149]
	v_pk_fma_f32 v[142:143], v[26:27], v[192:193], v[142:143]
	v_pk_fma_f32 v[140:141], v[24:25], v[190:191], v[140:141]
	v_lshl_add_u64 v[146:147], v[144:145], 2, s[28:29]
	v_mov_b32_e32 v202, 0
	s_and_b64 vcc, exec, s[8:9]
	v_mov_b32_e32 v206, 0
	global_store_dwordx4 v[146:147], v[136:139], off
	global_store_dwordx4 v[146:147], v[140:143], off offset:16
	s_waitcnt vmcnt(0)
	s_cbranch_vccnz .LBB0_501
	v_pk_mul_f32 v[148:149], v[184:185], v[138:139]
	v_pk_mul_f32 v[146:147], v[182:183], v[136:137]
	v_lshl_add_u64 v[144:145], v[144:145], 1, s[26:27]
	v_pk_mul_f32 v[150:151], v[188:189], v[142:143]
	v_pk_mul_f32 v[152:153], v[186:187], v[140:141]
	v_cvt_pk_bf16_f32 v146, v146, v147
	v_cvt_pk_bf16_f32 v147, v148, v149
	s_nop 0
	v_cvt_pk_bf16_f32 v148, v152, v153
	v_cvt_pk_bf16_f32 v149, v150, v151
	global_store_dwordx4 v[144:145], v[146:149], off
	v_mov_b32_e32 v145, v140
	v_mov_b32_e32 v140, v137
	v_mov_b32_e32 v144, v136
	v_pk_mul_f32 v[136:137], v[140:141], v[140:141]
	v_mov_b32_e32 v141, v142
	v_mov_b32_e32 v142, v139
	v_mov_b32_e32 v140, v138
	v_pk_mul_f32 v[138:139], v[142:143], v[142:143]
	v_pk_fma_f32 v[136:137], v[144:145], v[144:145], v[136:137]
	v_pk_fma_f32 v[138:139], v[140:141], v[140:141], v[138:139]
	s_nop 0
	v_pk_add_f32 v[136:137], v[136:137], v[138:139]
	s_nop 0
	v_add_f32_e32 v206, v136, v137
.LBB0_501:
	v_add_u32_e32 v176, 0x2c000, v176
	s_waitcnt vmcnt(0)
	v_pk_fma_f32 v[134:135], v[14:15], v[194:195], v[134:135]
	v_pk_fma_f32 v[132:133], v[12:13], v[196:197], v[132:133]
	v_pk_fma_f32 v[130:131], v[10:11], v[192:193], v[130:131]
	v_pk_fma_f32 v[128:129], v[8:9], v[190:191], v[128:129]
	v_lshl_add_u64 v[136:137], v[176:177], 2, s[28:29]
	s_and_b64 vcc, exec, s[8:9]
	global_store_dwordx4 v[136:137], v[132:135], off
	global_store_dwordx4 v[136:137], v[128:131], off offset:16
	s_waitcnt vmcnt(0)
	s_cbranch_vccnz .LBB0_503
	v_pk_mul_f32 v[138:139], v[184:185], v[134:135]
	v_pk_mul_f32 v[136:137], v[182:183], v[132:133]
	v_pk_mul_f32 v[140:141], v[188:189], v[130:131]
	v_pk_mul_f32 v[142:143], v[186:187], v[128:129]
	v_cvt_pk_bf16_f32 v136, v136, v137
	v_cvt_pk_bf16_f32 v137, v138, v139
	s_nop 0
	v_cvt_pk_bf16_f32 v138, v142, v143
	v_cvt_pk_bf16_f32 v139, v140, v141
	v_lshl_add_u64 v[140:141], v[176:177], 1, s[26:27]
	global_store_dwordx4 v[140:141], v[136:139], off
	s_nop 1
	v_mov_b32_e32 v137, v128
	v_mov_b32_e32 v128, v133
	v_mov_b32_e32 v133, v130
	v_mov_b32_e32 v130, v135
	v_mov_b32_e32 v136, v132
	v_pk_mul_f32 v[128:129], v[128:129], v[128:129]
	v_mov_b32_e32 v132, v134
	v_pk_mul_f32 v[130:131], v[130:131], v[130:131]
	v_pk_fma_f32 v[128:129], v[136:137], v[136:137], v[128:129]
	v_pk_fma_f32 v[130:131], v[132:133], v[132:133], v[130:131]
	s_nop 0
	v_pk_add_f32 v[128:129], v[128:129], v[130:131]
	s_nop 0
	v_add_f32_e32 v202, v128, v129

;     static __device__ __forceinline__ void run(const f32x4 (&acc)[2][2][4][2], const Unit& u, int wr, int wc, int fr, int fq, const float* xin, float* xout, const float* gate, float gs, const float* lazy_ssq, const float* lazy_g, ...
;     ...
;         for (int bj = 0; bj < 2; ++bj) {
;             const unsigned col = col0 + bj * HALF;
;             f32x4 gv[2], lg[2], wv[2], w2[2];
; #pragma unroll
;             for (int n = 0; n < 2; ++n) {
;                 gv[n] = *(const f32x4*)(gate + (b * 9216u + col + 4 * n)) * gs;
;                 lg[n] = (f32x4){1.f, 1.f, 1.f, 1.f}; if (LAZY) lg[n] = *(const f32x4*)(lazy_g + col + 4 * n);
;                 wv[n] = (f32x4){0.f, 0.f, 0.f, 0.f}; w2[n] = (f32x4){1.f, 1.f, 1.f, 1.f};
;                 if (aout) { wv[n] = *(const f32x4*)(wg + col + 4 * n) * (*(const f32x4*)(wsc + (b * 9216u + col + 4 * n)) + 1.0f); if (WG2) { w2[n] = *(const f32x4*)(wg2 + col + 4 * n); wv[n] = wv[n] * w2[n]; } }
;             }
;             f32x4 xq[2][2][2];
;     ...
;             constexpr bool DEEP = !LAZY && !WG2;
;             if (DEEP) RES_LD(0, 0);
; #pragma unroll
;             for (int pp = 0; pp < 4; ++pp) {
;                 if (DEEP) { if (pp < 3) RES_LD((pp + 1) & 1, pp + 1); } else RES_LD(pp & 1, pp);
; #pragma unroll
;                 for (int j = 0; j < 2; ++j) { const int i_ = 2 * pp + j, ai = i_ >> 2, m = i_ & 3; const unsigned off = (row0 + ai * HALF + m * 16) * 1024u + col;
;                     const f32x4 xi0 = xq[pp & 1][j][0], xi1 = xq[pp & 1][j][1];
;                     f32x4 xo0 = gv[0] * acc[ai][bj][m][0], xo1 = gv[1] * acc[ai][bj][m][1];
;                     if (LAZY) { xo0 = xo0 + xi0 * lg[0] * rl[ai][m]; xo1 = xo1 + xi1 * lg[1] * rl[ai][m]; } else { xo0 = xo0 + xi0; xo1 = xo1 + xi1; }
;                     *(f32x4*)(xout + off) = xo0; *(f32x4*)(xout + off + 4) = xo1;
;                     if (aout) { const f32x4 a0 = xo0 * wv[0], a1 = xo1 * wv[1]; u32x4 w; w.x = cvt_pk_bf16(a0[0], a0[1]); w.y = cvt_pk_bf16(a0[2], a0[3]); w.z = cvt_pk_bf16(a1[0], a1[1]); w.w = cvt_pk_bf16(a1[2], a1[3]);
;                         *(u32x4*)(aout + off) = w;
;                         sq[ai][m] += ((xo0[0] * xo0[0] + xo0[1] * xo0[1]) + (xo0[2] * xo0[2] + xo0[3] * xo0[3])) + ((xo1[0] * xo1[0] + xo1[1] * xo1[1]) + (xo1[2] * xo1[2] + xo1[3] * xo1[3]));
.LBB0_507:
	v_add_u32_e32 v176, v209, v207
	v_lshlrev_b64 v[214:215], 2, v[176:177]
	v_lshl_add_u64 v[128:129], s[34:35], 0, v[214:215]
	v_add_u32_e32 v198, 0x4000, v176
	v_mov_b32_e32 v199, v177
	global_load_dwordx4 v[210:213], v[128:129], off offset:16
	global_load_dwordx4 v[232:235], v[128:129], off
	v_lshl_add_u64 v[128:129], v[198:199], 2, s[34:35]
	v_add_u32_e32 v196, 0x8000, v176
	v_mov_b32_e32 v197, v177
	v_add_u32_e32 v194, 0xc000, v176
	v_mov_b32_e32 v195, v177
	global_load_dwordx4 v[132:135], v[128:129], off offset:16
	global_load_dwordx4 v[152:155], v[128:129], off
	v_lshl_add_u64 v[128:129], v[196:197], 2, s[34:35]
	v_lshl_add_u64 v[136:137], v[194:195], 2, s[34:35]
	global_load_dwordx4 v[144:147], v[128:129], off offset:16
	global_load_dwordx4 v[148:151], v[128:129], off
	s_nop 0
	global_load_dwordx4 v[128:131], v[136:137], off offset:16
	s_nop 0
	global_load_dwordx4 v[136:139], v[136:137], off
	s_mov_b32 s37, s36
	s_mov_b32 s38, s36
	s_mov_b32 s39, s36
	s_waitcnt vmcnt(8)
	v_pk_mul_f32 v[188:189], s[38:39], v[158:159]
	v_pk_mul_f32 v[174:175], s[36:37], v[156:157]
	v_pk_mul_f32 v[190:191], s[38:39], v[142:143]
	v_pk_mul_f32 v[192:193], s[36:37], v[140:141]
	s_and_b64 vcc, exec, s[8:9]
	v_lshl_add_u64 v[214:215], s[28:29], 0, v[214:215]
	s_waitcnt vmcnt(0)
	v_pk_fma_f32 v[142:143], v[114:115], v[188:189], v[212:213]
	s_waitcnt vmcnt(0)
	v_pk_fma_f32 v[158:159], v[118:119], v[190:191], v[234:235]
	v_pk_fma_f32 v[156:157], v[116:117], v[192:193], v[232:233]
	v_pk_fma_f32 v[140:141], v[112:113], v[174:175], v[210:211]
	global_store_dwordx4 v[214:215], v[156:159], off
	global_store_dwordx4 v[214:215], v[140:143], off offset:16
	s_waitcnt vmcnt(0)
	s_cbranch_vccnz .LBB0_509
	v_pk_mul_f32 v[212:213], v[184:185], v[158:159]
	v_pk_mul_f32 v[210:211], v[182:183], v[156:157]
	v_pk_mul_f32 v[214:215], v[186:187], v[142:143]
	v_pk_mul_f32 v[232:233], v[180:181], v[140:141]
	v_cvt_pk_bf16_f32 v210, v210, v211
	v_cvt_pk_bf16_f32 v211, v212, v213
	s_nop 0
	v_cvt_pk_bf16_f32 v212, v232, v233
	v_cvt_pk_bf16_f32 v213, v214, v215
	v_lshl_add_u64 v[214:215], v[176:177], 1, s[26:27]
	global_store_dwordx4 v[214:215], v[210:213], off
	s_nop 1
	v_mov_b32_e32 v211, v140
	v_mov_b32_e32 v140, v157
	v_mov_b32_e32 v157, v142
	v_mov_b32_e32 v142, v159
	v_mov_b32_e32 v210, v156
	v_pk_mul_f32 v[140:141], v[140:141], v[140:141]
	v_mov_b32_e32 v156, v158
	v_pk_mul_f32 v[142:143], v[142:143], v[142:143]
	v_pk_fma_f32 v[140:141], v[210:211], v[210:211], v[140:141]
	v_pk_fma_f32 v[142:143], v[156:157], v[156:157], v[142:143]
	s_nop 0
	v_pk_add_f32 v[140:141], v[140:141], v[142:143]
	s_nop 0
	v_add_f32_e32 v140, v140, v141
	v_add_f32_e32 v173, v173, v140
.LBB0_509:
	s_waitcnt vmcnt(0)
	v_pk_fma_f32 v[142:143], v[102:103], v[190:191], v[154:155]
	v_pk_fma_f32 v[140:141], v[100:101], v[192:193], v[152:153]
	v_pk_fma_f32 v[134:135], v[98:99], v[188:189], v[134:135]
	v_pk_fma_f32 v[132:133], v[96:97], v[174:175], v[132:133]
	v_lshl_add_u64 v[152:153], v[198:199], 2, s[28:29]
	s_and_b64 vcc, exec, s[8:9]
	global_store_dwordx4 v[152:153], v[140:143], off
	global_store_dwordx4 v[152:153], v[132:135], off offset:16
	s_waitcnt vmcnt(0)
	s_cbranch_vccnz .LBB0_511
	v_pk_mul_f32 v[154:155], v[184:185], v[142:143]
	v_pk_mul_f32 v[152:153], v[182:183], v[140:141]
	v_pk_mul_f32 v[156:157], v[186:187], v[134:135]
	v_pk_mul_f32 v[158:159], v[180:181], v[132:133]
	v_cvt_pk_bf16_f32 v152, v152, v153
	v_cvt_pk_bf16_f32 v153, v154, v155
	s_nop 0
	v_cvt_pk_bf16_f32 v154, v158, v159
	v_cvt_pk_bf16_f32 v155, v156, v157
	v_lshl_add_u64 v[156:157], v[198:199], 1, s[26:27]
	global_store_dwordx4 v[156:157], v[152:155], off
	s_nop 1
	v_mov_b32_e32 v153, v132
	v_mov_b32_e32 v132, v141
	v_mov_b32_e32 v141, v134
	v_mov_b32_e32 v134, v143
	v_mov_b32_e32 v152, v140
	v_pk_mul_f32 v[132:133], v[132:133], v[132:133]
	v_mov_b32_e32 v140, v142
	v_pk_mul_f32 v[134:135], v[134:135], v[134:135]
	v_pk_fma_f32 v[132:133], v[152:153], v[152:153], v[132:133]
	v_pk_fma_f32 v[134:135], v[140:141], v[140:141], v[134:135]
	s_nop 0
	v_pk_add_f32 v[132:133], v[132:133], v[134:135]
	s_nop 0
	v_add_f32_e32 v132, v132, v133
	v_add_f32_e32 v204, v204, v132
.LBB0_511:
	v_add_u32_e32 v198, v208, v209
	v_mov_b32_e32 v199, v177
	v_lshl_add_u64 v[132:133], v[198:199], 2, s[34:35]
	global_load_dwordx4 v[152:155], v[132:133], off offset:16
	global_load_dwordx4 v[156:159], v[132:133], off
	v_add_u32_e32 v132, 0x4000, v198
	v_mov_b32_e32 v133, v177
	v_lshl_add_u64 v[140:141], v[132:133], 2, s[34:35]
	global_load_dwordx4 v[132:135], v[140:141], off offset:16
	s_nop 0
	global_load_dwordx4 v[140:143], v[140:141], off
	s_waitcnt vmcnt(0)
	v_pk_fma_f32 v[150:151], v[86:87], v[190:191], v[150:151]
	v_pk_fma_f32 v[148:149], v[84:85], v[192:193], v[148:149]
	v_pk_fma_f32 v[146:147], v[82:83], v[188:189], v[146:147]
	v_pk_fma_f32 v[144:145], v[80:81], v[174:175], v[144:145]
	v_lshl_add_u64 v[208:209], v[196:197], 2, s[28:29]
	s_and_b64 vcc, exec, s[8:9]
	global_store_dwordx4 v[208:209], v[148:151], off
	global_store_dwordx4 v[208:209], v[144:147], off offset:16
	s_waitcnt vmcnt(0)
	s_cbranch_vccnz .LBB0_513
	v_pk_mul_f32 v[210:211], v[184:185], v[150:151]
	v_pk_mul_f32 v[208:209], v[182:183], v[148:149]
	v_lshl_add_u64 v[196:197], v[196:197], 1, s[26:27]
	v_pk_mul_f32 v[212:213], v[186:187], v[146:147]
	v_pk_mul_f32 v[214:215], v[180:181], v[144:145]
	v_cvt_pk_bf16_f32 v208, v208, v209
	v_cvt_pk_bf16_f32 v209, v210, v211
	s_nop 0
	v_cvt_pk_bf16_f32 v210, v214, v215
	v_cvt_pk_bf16_f32 v211, v212, v213
	global_store_dwordx4 v[196:197], v[208:211], off
	v_mov_b32_e32 v197, v144
	v_mov_b32_e32 v144, v149
	v_mov_b32_e32 v149, v146
	v_mov_b32_e32 v146, v151
	v_mov_b32_e32 v196, v148
	v_pk_mul_f32 v[144:145], v[144:145], v[144:145]
	v_mov_b32_e32 v148, v150
	v_pk_mul_f32 v[146:147], v[146:147], v[146:147]
	v_pk_fma_f32 v[144:145], v[196:197], v[196:197], v[144:145]
	v_pk_fma_f32 v[146:147], v[148:149], v[148:149], v[146:147]
	s_nop 0
	v_pk_add_f32 v[144:145], v[144:145], v[146:147]
	s_nop 0
	v_add_f32_e32 v144, v144, v145
	v_add_f32_e32 v205, v205, v144
; __device__ __forceinline__ unsigned cvt_pk_bf16(float lo, float hi) { unsigned r; asm volatile("v_cvt_pk_bf16_f32 %0, %1, %2" : "=v"(r) : "v"(lo), "v"(hi)); return r; }
; #define RES_LD(buf, pp) do { _Pragma("unroll") for (int j = 0; j < 2; ++j) { const int i_ = 2 * (pp) + j; const unsigned off_ = (row0 + (i_ >> 2) * HALF + (i_ & 3) * 16) * 1024u + col; \
;                 xq[buf][j][0] = *(const f32x4*)(xin + off_); xq[buf][j][1] = *(const f32x4*)(xin + off_ + 4); } } while (0)
;     static __device__ __forceinline__ void run(const f32x4 (&acc)[2][2][4][2], const Unit& u, int wr, int wc, int fr, int fq, const float* xin, float* xout, const float* gate, float gs, const float* lazy_ssq, const float* lazy_g, ...
;     ...
;             constexpr bool DEEP = !LAZY && !WG2;
;             if (DEEP) RES_LD(0, 0);
; #pragma unroll
;             for (int pp = 0; pp < 4; ++pp) {
;                 if (DEEP) { if (pp < 3) RES_LD((pp + 1) & 1, pp + 1); } else RES_LD(pp & 1, pp);
; #pragma unroll
;                 for (int j = 0; j < 2; ++j) { const int i_ = 2 * pp + j, ai = i_ >> 2, m = i_ & 3; const unsigned off = (row0 + ai * HALF + m * 16) * 1024u + col;
;                     const f32x4 xi0 = xq[pp & 1][j][0], xi1 = xq[pp & 1][j][1];
;                     f32x4 xo0 = gv[0] * acc[ai][bj][m][0], xo1 = gv[1] * acc[ai][bj][m][1];
;                     if (LAZY) { xo0 = xo0 + xi0 * lg[0] * rl[ai][m]; xo1 = xo1 + xi1 * lg[1] * rl[ai][m]; } else { xo0 = xo0 + xi0; xo1 = xo1 + xi1; }
;                     *(f32x4*)(xout + off) = xo0; *(f32x4*)(xout + off + 4) = xo1;
;                     if (aout) { const f32x4 a0 = xo0 * wv[0], a1 = xo1 * wv[1]; u32x4 w; w.x = cvt_pk_bf16(a0[0], a0[1]); w.y = cvt_pk_bf16(a0[2], a0[3]); w.z = cvt_pk_bf16(a1[0], a1[1]); w.w = cvt_pk_bf16(a1[2], a1[3]);
;                         *(u32x4*)(aout + off) = w;
;                         sq[ai][m] += ((xo0[0] * xo0[0] + xo0[1] * xo0[1]) + (xo0[2] * xo0[2] + xo0[3] * xo0[3])) + ((xo1[0] * xo1[0] + xo1[1] * xo1[1]) + (xo1[2] * xo1[2] + xo1[3] * xo1[3]));
;                         if (WG2) { const f32x4 b0 = xo0 * w2[0], b1 = xo1 * w2[1]; sqb[ai][m] += ((b0[0] * b0[0] + b0[1] * b0[1]) + (b0[2] * b0[2] + b0[3] * b0[3])) + ((b1[0] * b1[0] + b1[1] * b1[1]) + (b1[2] * b1[2] + b1[3] * b1[3])); } } }
.LBB0_513:
	s_waitcnt vmcnt(0)
	v_pk_fma_f32 v[138:139], v[70:71], v[190:191], v[138:139]
	v_pk_fma_f32 v[136:137], v[68:69], v[192:193], v[136:137]
	v_pk_fma_f32 v[130:131], v[66:67], v[188:189], v[130:131]
	v_pk_fma_f32 v[128:129], v[64:65], v[174:175], v[128:129]
	v_lshl_add_u64 v[144:145], v[194:195], 2, s[28:29]
	s_and_b64 vcc, exec, s[8:9]
	global_store_dwordx4 v[144:145], v[136:139], off
	global_store_dwordx4 v[144:145], v[128:131], off offset:16
	s_waitcnt vmcnt(0)
	s_cbranch_vccnz .LBB0_515
	v_pk_mul_f32 v[146:147], v[184:185], v[138:139]
	v_pk_mul_f32 v[144:145], v[182:183], v[136:137]
	v_pk_mul_f32 v[148:149], v[186:187], v[130:131]
	v_pk_mul_f32 v[150:151], v[180:181], v[128:129]
	v_cvt_pk_bf16_f32 v144, v144, v145
	v_cvt_pk_bf16_f32 v145, v146, v147
	s_nop 0
	v_cvt_pk_bf16_f32 v146, v150, v151
	v_cvt_pk_bf16_f32 v147, v148, v149
	v_lshl_add_u64 v[148:149], v[194:195], 1, s[26:27]
	global_store_dwordx4 v[148:149], v[144:147], off
	s_nop 1
	v_mov_b32_e32 v145, v128
	v_mov_b32_e32 v128, v137
	v_mov_b32_e32 v137, v130
	v_mov_b32_e32 v130, v139
	v_mov_b32_e32 v144, v136
	v_pk_mul_f32 v[128:129], v[128:129], v[128:129]
	v_mov_b32_e32 v136, v138
	v_pk_mul_f32 v[130:131], v[130:131], v[130:131]
	v_pk_fma_f32 v[128:129], v[144:145], v[144:145], v[128:129]
	v_pk_fma_f32 v[130:131], v[136:137], v[136:137], v[130:131]
	s_nop 0
	v_pk_add_f32 v[128:129], v[128:129], v[130:131]
	s_nop 0
	v_add_f32_e32 v128, v128, v129
	v_add_f32_e32 v203, v203, v128
.LBB0_515:
	s_nop 0
	v_add_u32_e32 v128, 0x8000, v198
	v_mov_b32_e32 v129, v177
	v_lshl_add_u64 v[128:129], v[128:129], 2, s[34:35]
	global_load_dwordx4 v[144:147], v[128:129], off offset:16
	global_load_dwordx4 v[148:151], v[128:129], off
	v_add_u32_e32 v128, 0xc000, v198
	v_mov_b32_e32 v129, v177
	v_lshl_add_u64 v[136:137], v[128:129], 2, s[34:35]
	global_load_dwordx4 v[128:131], v[136:137], off offset:16
	s_nop 0
	global_load_dwordx4 v[136:139], v[136:137], off
	v_add_u32_e32 v194, 0x20000, v176
	v_mov_b32_e32 v195, v177
	s_waitcnt vmcnt(0)
	v_pk_fma_f32 v[158:159], v[54:55], v[190:191], v[158:159]
	v_pk_fma_f32 v[156:157], v[52:53], v[192:193], v[156:157]
	v_pk_fma_f32 v[154:155], v[50:51], v[188:189], v[154:155]
	v_pk_fma_f32 v[152:153], v[48:49], v[174:175], v[152:153]
	v_lshl_add_u64 v[196:197], v[194:195], 2, s[28:29]
	s_and_b64 vcc, exec, s[8:9]
	global_store_dwordx4 v[196:197], v[156:159], off
	global_store_dwordx4 v[196:197], v[152:155], off offset:16
	s_waitcnt vmcnt(0)
	s_cbranch_vccnz .LBB0_517
	v_pk_mul_f32 v[198:199], v[184:185], v[158:159]
	v_pk_mul_f32 v[196:197], v[182:183], v[156:157]
	v_lshl_add_u64 v[194:195], v[194:195], 1, s[26:27]
	v_pk_mul_f32 v[208:209], v[186:187], v[154:155]
	v_pk_mul_f32 v[210:211], v[180:181], v[152:153]
	v_cvt_pk_bf16_f32 v196, v196, v197
	v_cvt_pk_bf16_f32 v197, v198, v199
	s_nop 0
	v_cvt_pk_bf16_f32 v198, v210, v211
	v_cvt_pk_bf16_f32 v199, v208, v209
	global_store_dwordx4 v[194:195], v[196:199], off
	v_mov_b32_e32 v195, v152
	v_mov_b32_e32 v152, v157
	v_mov_b32_e32 v157, v154
	v_mov_b32_e32 v154, v159
	v_mov_b32_e32 v194, v156
	v_pk_mul_f32 v[152:153], v[152:153], v[152:153]
	v_mov_b32_e32 v156, v158
	v_pk_mul_f32 v[154:155], v[154:155], v[154:155]
	v_pk_fma_f32 v[152:153], v[194:195], v[194:195], v[152:153]
	v_pk_fma_f32 v[154:155], v[156:157], v[156:157], v[154:155]
	s_nop 0
	v_pk_add_f32 v[152:153], v[152:153], v[154:155]
	s_nop 0
	v_add_f32_e32 v152, v152, v153
	v_add_f32_e32 v201, v201, v152
; __device__ __forceinline__ unsigned cvt_pk_bf16(float lo, float hi) { unsigned r; asm volatile("v_cvt_pk_bf16_f32 %0, %1, %2" : "=v"(r) : "v"(lo), "v"(hi)); return r; }
;     static __device__ __forceinline__ void run(const f32x4 (&acc)[2][2][4][2], const Unit& u, int wr, int wc, int fr, int fq, const float* xin, float* xout, const float* gate, float gs, const float* lazy_ssq, const float* lazy_g, ...
;     ...
;                 for (int j = 0; j < 2; ++j) { const int i_ = 2 * pp + j, ai = i_ >> 2, m = i_ & 3; const unsigned off = (row0 + ai * HALF + m * 16) * 1024u + col;
;                     const f32x4 xi0 = xq[pp & 1][j][0], xi1 = xq[pp & 1][j][1];
;                     f32x4 xo0 = gv[0] * acc[ai][bj][m][0], xo1 = gv[1] * acc[ai][bj][m][1];
;                     if (LAZY) { xo0 = xo0 + xi0 * lg[0] * rl[ai][m]; xo1 = xo1 + xi1 * lg[1] * rl[ai][m]; } else { xo0 = xo0 + xi0; xo1 = xo1 + xi1; }
;                     *(f32x4*)(xout + off) = xo0; *(f32x4*)(xout + off + 4) = xo1;
;                     if (aout) { const f32x4 a0 = xo0 * wv[0], a1 = xo1 * wv[1]; u32x4 w; w.x = cvt_pk_bf16(a0[0], a0[1]); w.y = cvt_pk_bf16(a0[2], a0[3]); w.z = cvt_pk_bf16(a1[0], a1[1]); w.w = cvt_pk_bf16(a1[2], a1[3]);
;                         *(u32x4*)(aout + off) = w;
;                         sq[ai][m] += ((xo0[0] * xo0[0] + xo0[1] * xo0[1]) + (xo0[2] * xo0[2] + xo0[3] * xo0[3])) + ((xo1[0] * xo1[0] + xo1[1] * xo1[1]) + (xo1[2] * xo1[2] + xo1[3] * xo1[3]));
;                         if (WG2) { const f32x4 b0 = xo0 * w2[0], b1 = xo1 * w2[1]; sqb[ai][m] += ((b0[0] * b0[0] + b0[1] * b0[1]) + (b0[2] * b0[2] + b0[3] * b0[3])) + ((b1[0] * b1[0] + b1[1] * b1[1]) + (b1[2] * b1[2] + b1[3] * b1[3])); } } }
.LBB0_517:
	s_nop 0
	v_add_u32_e32 v152, 0x24000, v176
	v_mov_b32_e32 v153, v177
	s_waitcnt vmcnt(0)
	v_pk_fma_f32 v[142:143], v[38:39], v[190:191], v[142:143]
	v_pk_fma_f32 v[140:141], v[36:37], v[192:193], v[140:141]
	v_pk_fma_f32 v[134:135], v[34:35], v[188:189], v[134:135]
	v_pk_fma_f32 v[132:133], v[32:33], v[174:175], v[132:133]
	v_lshl_add_u64 v[154:155], v[152:153], 2, s[28:29]
	s_and_b64 vcc, exec, s[8:9]
	global_store_dwordx4 v[154:155], v[140:143], off
	global_store_dwordx4 v[154:155], v[132:135], off offset:16
	s_waitcnt vmcnt(0)
	s_cbranch_vccnz .LBB0_519
	v_pk_mul_f32 v[156:157], v[184:185], v[142:143]
	v_pk_mul_f32 v[154:155], v[182:183], v[140:141]
	v_lshl_add_u64 v[152:153], v[152:153], 1, s[26:27]
	v_pk_mul_f32 v[158:159], v[186:187], v[134:135]
	v_pk_mul_f32 v[194:195], v[180:181], v[132:133]
	v_cvt_pk_bf16_f32 v154, v154, v155
	v_cvt_pk_bf16_f32 v155, v156, v157
	s_nop 0
	v_cvt_pk_bf16_f32 v156, v194, v195
	v_cvt_pk_bf16_f32 v157, v158, v159
	global_store_dwordx4 v[152:153], v[154:157], off
	v_mov_b32_e32 v153, v132
	v_mov_b32_e32 v132, v141
	v_mov_b32_e32 v141, v134
	v_mov_b32_e32 v134, v143
	v_mov_b32_e32 v152, v140
	v_pk_mul_f32 v[132:133], v[132:133], v[132:133]
	v_mov_b32_e32 v140, v142
	v_pk_mul_f32 v[134:135], v[134:135], v[134:135]
	v_pk_fma_f32 v[132:133], v[152:153], v[152:153], v[132:133]
	v_pk_fma_f32 v[134:135], v[140:141], v[140:141], v[134:135]
	s_nop 0
	v_pk_add_f32 v[132:133], v[132:133], v[134:135]
	s_nop 0
	v_add_f32_e32 v132, v132, v133
	v_add_f32_e32 v200, v200, v132
.LBB0_519:
	v_add_u32_e32 v152, 0x28000, v176
	v_mov_b32_e32 v153, v177
	s_waitcnt vmcnt(0)
	v_pk_fma_f32 v[134:135], v[22:23], v[190:191], v[150:151]
	v_pk_fma_f32 v[132:133], v[20:21], v[192:193], v[148:149]
	v_pk_fma_f32 v[142:143], v[18:19], v[188:189], v[146:147]
	v_pk_fma_f32 v[140:141], v[16:17], v[174:175], v[144:145]
	v_lshl_add_u64 v[144:145], v[152:153], 2, s[28:29]
	s_and_b64 vcc, exec, s[8:9]
	global_store_dwordx4 v[144:145], v[132:135], off
	global_store_dwordx4 v[144:145], v[140:143], off offset:16
	s_waitcnt vmcnt(0)
	s_cbranch_vccnz .LBB0_521
	v_pk_mul_f32 v[146:147], v[184:185], v[134:135]
	v_pk_mul_f32 v[144:145], v[182:183], v[132:133]
	v_pk_mul_f32 v[148:149], v[186:187], v[142:143]
	v_pk_mul_f32 v[150:151], v[180:181], v[140:141]
	v_cvt_pk_bf16_f32 v144, v144, v145
	v_cvt_pk_bf16_f32 v145, v146, v147
	s_nop 0
	v_cvt_pk_bf16_f32 v146, v150, v151
	v_cvt_pk_bf16_f32 v147, v148, v149
	v_lshl_add_u64 v[148:149], v[152:153], 1, s[26:27]
	global_store_dwordx4 v[148:149], v[144:147], off
	s_nop 1
	v_mov_b32_e32 v145, v140
	v_mov_b32_e32 v140, v133
	v_mov_b32_e32 v144, v132
	v_pk_mul_f32 v[132:133], v[140:141], v[140:141]
	v_mov_b32_e32 v141, v142
	v_mov_b32_e32 v142, v135
	v_mov_b32_e32 v140, v134
	v_pk_mul_f32 v[134:135], v[142:143], v[142:143]
	v_pk_fma_f32 v[132:133], v[144:145], v[144:145], v[132:133]
	v_pk_fma_f32 v[134:135], v[140:141], v[140:141], v[134:135]
	s_nop 0
	v_pk_add_f32 v[132:133], v[132:133], v[134:135]
	s_nop 0
	v_add_f32_e32 v132, v132, v133
	v_add_f32_e32 v206, v206, v132
.LBB0_521:
	v_add_u32_e32 v176, 0x2c000, v176
	s_waitcnt vmcnt(0)
	v_pk_fma_f32 v[134:135], v[6:7], v[190:191], v[138:139]
	v_pk_fma_f32 v[132:133], v[4:5], v[192:193], v[136:137]
	v_pk_fma_f32 v[130:131], v[2:3], v[188:189], v[130:131]
	v_pk_fma_f32 v[128:129], v[0:1], v[174:175], v[128:129]
	v_lshl_add_u64 v[136:137], v[176:177], 2, s[28:29]
	s_and_b64 vcc, exec, s[8:9]
	global_store_dwordx4 v[136:137], v[132:135], off
	global_store_dwordx4 v[136:137], v[128:131], off offset:16
	s_waitcnt vmcnt(0)
	s_cbranch_vccnz .LBB0_523
	v_pk_mul_f32 v[138:139], v[184:185], v[134:135]
	v_pk_mul_f32 v[136:137], v[182:183], v[132:133]
	v_pk_mul_f32 v[140:141], v[186:187], v[130:131]
	v_pk_mul_f32 v[142:143], v[180:181], v[128:129]
	v_cvt_pk_bf16_f32 v136, v136, v137
	v_cvt_pk_bf16_f32 v137, v138, v139
	s_nop 0
	v_cvt_pk_bf16_f32 v138, v142, v143
	v_cvt_pk_bf16_f32 v139, v140, v141
	v_lshl_add_u64 v[140:141], v[176:177], 1, s[26:27]
	global_store_dwordx4 v[140:141], v[136:139], off
	s_nop 1
	v_mov_b32_e32 v137, v128
	v_mov_b32_e32 v128, v133
	v_mov_b32_e32 v133, v130
	v_mov_b32_e32 v130, v135
	v_mov_b32_e32 v136, v132
	v_pk_mul_f32 v[128:129], v[128:129], v[128:129]
	v_mov_b32_e32 v132, v134
	v_pk_mul_f32 v[130:131], v[130:131], v[130:131]
	v_pk_fma_f32 v[128:129], v[136:137], v[136:137], v[128:129]
	v_pk_fma_f32 v[130:131], v[132:133], v[132:133], v[130:131]
	s_nop 0
	v_pk_add_f32 v[128:129], v[128:129], v[130:131]
	s_nop 0
	v_add_f32_e32 v128, v128, v129
	v_add_f32_e32 v202, v202, v128
